# v34 + SB waves 4-7 delayed start + GU GEMM peeled first K-iteration after each epilogue (store-tolerant waits, As11 stage hoisted)
# speedup vs baseline: 1.0172x; 1.0031x over previous
; #define PG8_LAS __attribute__((address_space(3)))
; __device__ __forceinline__ unsigned cvt_pk_bf16(float lo, float hi) { unsigned r; asm volatile("v_cvt_pk_bf16_f32 %0, %1, %2" : "=v"(r) : "v"(lo), "v"(hi)); return r; }
; __device__ __forceinline__ float silu_mul(float g, float u) { return g * u * __builtin_amdgcn_rcpf(1.0f + __builtin_amdgcn_exp2f(-1.4426950408889634f * g)); }
;     __device__ __forceinline__ void operator()(const f32x4 (&acc)[2][2][4][2], const Unit& u, int wr, int wc, int fr, int fq) const {
;         const int row0 = u.pm * BM + wr * 64 + fr, col0 = u.pn * HALF + wc * 32 + 8 * fq;
;         float rsv[8]; { const PG8_LAS float* t_ = rt.rows(u.pm) + wr * 64 + fr;
; #pragma unroll
;             for (int it = 0; it < 8; ++it) rsv[it] = t_[(it >> 2) * HALF + (it & 3) * 16]; }
; #pragma unroll
;         for (int ai = 0; ai < 2; ++ai)
; #pragma unroll
;             for (int m = 0; m < 4; ++m) {
;                 const int row = row0 + ai * HALF + m * 16; const float rs = rsv[ai * 4 + m];
;                 const f32x4 g0 = acc[ai][0][m][0] * rs, g1 = acc[ai][0][m][1] * rs, u0 = acc[ai][1][m][0] * rs, u1 = acc[ai][1][m][1] * rs;
;                 u32x4e w;
;                 w.x = cvt_pk_bf16(silu_mul(g0[0], u0[0]), silu_mul(g0[1], u0[1])); w.y = cvt_pk_bf16(silu_mul(g0[2], u0[2]), silu_mul(g0[3], u0[3]));
;                 w.z = cvt_pk_bf16(silu_mul(g1[0], u1[0]), silu_mul(g1[1], u1[1])); w.w = cvt_pk_bf16(silu_mul(g1[2], u1[2]), silu_mul(g1[3], u1[3]));
;                 *(u32x4e*)(O + (size_t)row * ldo + col0) = w;
;             }
; template <class Epi, class Sched, bool ALIGN_EPI = false, bool SP2 = false>
; __device__ __forceinline__ void gemm_phase(PG8_LAS unsigned char* lds, const Gemm g, const Sched& S, const Epi& E) {
;     ...
;     const char* cA = (const char*)g.A + (size_t)cur.pm * tstep; const char* cB = (const char*)g.Bt + (size_t)cur.pn * tstep;
;     ...
;             const char* a1 = cA + (size_t)(t + 1) * kstep;
.LBB0_402:
	s_add_u32 s14, s46, 0x40080
	s_addc_u32 s15, s41, 0
	v_lshl_add_u64 v[224:225], s[14:15], 0, v[134:135]
	s_add_i32 m0, s25, 0xc000
	v_lshl_add_u64 v[226:227], s[14:15], 0, v[136:137]
	global_load_lds_dwordx4 v[224:225], off
	s_add_i32 m0, s25, 0xe000
	s_nop 0
	global_load_lds_dwordx4 v[226:227], off
	s_cmp_eq_u32 s35, s16
	s_cselect_b32 s9, 0x200, s23
	s_cmp_lg_u32 s35, s17
	s_cselect_b32 s9, s9, 0x100
	s_cmp_lg_u32 s35, s18
	s_cselect_b32 s9, s9, 0
	v_lshl_add_u32 v138, s9, 2, v150
	ds_read2_b32 v[144:145], v138 offset1:16
	ds_read2_b32 v[142:143], v138 offset0:32 offset1:48
	ds_read2_b32 v[140:141], v138 offset0:128 offset1:144
	ds_read2_b32 v[138:139], v138 offset0:160 offset1:176
	v_lshl_or_b32 v146, s34, 7, v151
	s_waitcnt lgkmcnt(0)
	v_pk_mul_f32 v[124:125], v[124:125], v[144:145] op_sel_hi:[1,0]
	v_pk_mul_f32 v[116:117], v[116:117], v[144:145] op_sel_hi:[1,0]
	v_pk_mul_f32 v[126:127], v[126:127], v[144:145] op_sel_hi:[1,0]
	v_mul_f32_e32 v116, v124, v116
	v_mul_f32_e32 v124, 0xbfb8aa3b, v124
	v_exp_f32_e32 v124, v124
	v_mul_f32_e32 v117, v125, v117
	v_pk_mul_f32 v[118:119], v[118:119], v[144:145] op_sel_hi:[1,0]
	v_pk_mul_f32 v[120:121], v[120:121], v[144:145] op_sel_hi:[1,0]
	v_add_f32_e32 v124, 1.0, v124
	v_rcp_f32_e32 v124, v124
	v_pk_mul_f32 v[112:113], v[112:113], v[144:145] op_sel_hi:[1,0]
	v_pk_mul_f32 v[122:123], v[122:123], v[144:145] op_sel_hi:[1,0]
	v_mul_f32_e32 v112, v120, v112
	v_mul_f32_e32 v116, v116, v124
	v_mul_f32_e32 v124, 0xbfb8aa3b, v125
	v_exp_f32_e32 v124, v124
	v_mul_f32_e32 v113, v121, v113
	v_pk_mul_f32 v[114:115], v[114:115], v[144:145] op_sel_hi:[1,0]
	v_lshl_add_u32 v153, s35, 8, v148
	v_add_f32_e32 v124, 1.0, v124
	v_rcp_f32_e32 v124, v124
	v_ashrrev_i32_e32 v147, 31, v146
	v_pk_mul_f32 v[92:93], v[92:93], v[142:143] op_sel_hi:[1,0]
	v_pk_mul_f32 v[84:85], v[84:85], v[142:143] op_sel_hi:[1,0]
	v_mul_f32_e32 v117, v117, v124
	v_cvt_pk_bf16_f32 v116, v116, v117
	v_mul_f32_e32 v117, v126, v118
	v_mul_f32_e32 v118, 0xbfb8aa3b, v126
	v_exp_f32_e32 v118, v118
	v_pk_mul_f32 v[94:95], v[94:95], v[142:143] op_sel_hi:[1,0]
	v_pk_mul_f32 v[86:87], v[86:87], v[142:143] op_sel_hi:[1,0]
	v_pk_mul_f32 v[88:89], v[88:89], v[142:143] op_sel_hi:[1,0]
	v_add_f32_e32 v118, 1.0, v118
	v_rcp_f32_e32 v118, v118
	v_pk_mul_f32 v[90:91], v[90:91], v[142:143] op_sel_hi:[1,0]
	v_pk_mul_f32 v[60:61], v[60:61], v[140:141] op_sel_hi:[1,0]
	v_pk_mul_f32 v[52:53], v[52:53], v[140:141] op_sel_hi:[1,0]
	v_mul_f32_e32 v117, v117, v118
	v_mul_f32_e32 v118, v127, v119
	v_mul_f32_e32 v119, 0xbfb8aa3b, v127
	v_exp_f32_e32 v119, v119
	v_pk_mul_f32 v[62:63], v[62:63], v[140:141] op_sel_hi:[1,0]
	v_pk_mul_f32 v[54:55], v[54:55], v[140:141] op_sel_hi:[1,0]
	v_pk_mul_f32 v[56:57], v[56:57], v[140:141] op_sel_hi:[1,0]
	v_add_f32_e32 v119, 1.0, v119
	v_rcp_f32_e32 v119, v119
	v_pk_mul_f32 v[58:59], v[58:59], v[140:141] op_sel_hi:[1,0]
	v_pk_mul_f32 v[28:29], v[28:29], v[138:139] op_sel_hi:[1,0]
	v_pk_mul_f32 v[20:21], v[20:21], v[138:139] op_sel_hi:[1,0]
	v_mul_f32_e32 v118, v118, v119
	v_cvt_pk_bf16_f32 v117, v117, v118
	v_mul_f32_e32 v118, 0xbfb8aa3b, v120
	v_exp_f32_e32 v118, v118
	v_pk_mul_f32 v[30:31], v[30:31], v[138:139] op_sel_hi:[1,0]
	v_pk_mul_f32 v[22:23], v[22:23], v[138:139] op_sel_hi:[1,0]
	v_pk_mul_f32 v[24:25], v[24:25], v[138:139] op_sel_hi:[1,0]
	v_add_f32_e32 v118, 1.0, v118
	v_rcp_f32_e32 v118, v118
	v_pk_mul_f32 v[26:27], v[26:27], v[138:139] op_sel_hi:[1,0]
	s_andn2_b64 vcc, exec, s[38:39]
	v_mul_f32_e32 v112, v112, v118
	v_mul_f32_e32 v118, 0xbfb8aa3b, v121
	v_exp_f32_e32 v118, v118
	s_nop 0
	v_add_f32_e32 v118, 1.0, v118
	v_rcp_f32_e32 v118, v118
	s_nop 0
	v_mul_f32_e32 v113, v113, v118
	v_cvt_pk_bf16_f32 v118, v112, v113
	v_mul_f32_e32 v113, 0xbfb8aa3b, v122
	v_mul_f32_e32 v112, v122, v114
	v_exp_f32_e32 v113, v113
	v_mul_f32_e32 v114, 0xbfb8aa3b, v123
	v_exp_f32_e32 v114, v114
	v_add_f32_e32 v113, 1.0, v113
	v_rcp_f32_e32 v113, v113
	v_add_f32_e32 v114, 1.0, v114
	v_rcp_f32_e32 v114, v114
	v_mul_f32_e32 v112, v112, v113
	v_mul_f32_e32 v113, v123, v115
	v_mul_f32_e32 v113, v113, v114
	v_cvt_pk_bf16_f32 v119, v112, v113
	v_mov_b64_e32 v[112:113], s[90:91]
	v_mad_i64_i32 v[120:121], s[10:11], v153, s24, v[112:113]
	v_lshlrev_b64 v[114:115], 1, v[146:147]
	v_lshl_add_u64 v[120:121], v[120:121], 0, v[114:115]
	global_store_dwordx4 v[120:121], v[116:119], off
	s_nop 1
	v_or_b32_e32 v117, 16, v153
	v_mov_b32_e32 v116, v145
	v_pk_mul_f32 v[108:109], v[108:109], v[116:117] op_sel_hi:[1,0]
	v_pk_mul_f32 v[100:101], v[100:101], v[116:117] op_sel_hi:[1,0]
	v_pk_mul_f32 v[118:119], v[98:99], v[116:117] op_sel_hi:[1,0]
	v_pk_mul_f32 v[98:99], v[96:97], v[116:117] op_sel_hi:[1,0]
	v_mul_f32_e32 v97, 0xbfb8aa3b, v108
	v_mul_f32_e32 v96, v108, v100
	v_exp_f32_e32 v97, v97
	v_mul_f32_e32 v100, 0xbfb8aa3b, v109
	v_exp_f32_e32 v100, v100
	v_pk_mul_f32 v[110:111], v[110:111], v[116:117] op_sel_hi:[1,0]
	v_add_f32_e32 v97, 1.0, v97
	v_rcp_f32_e32 v97, v97
	v_add_f32_e32 v100, 1.0, v100
	v_rcp_f32_e32 v100, v100
	v_pk_mul_f32 v[102:103], v[102:103], v[116:117] op_sel_hi:[1,0]
	v_mul_f32_e32 v96, v96, v97
	v_mul_f32_e32 v97, v109, v101
	v_mul_f32_e32 v97, v97, v100
	v_mul_f32_e32 v100, 0xbfb8aa3b, v110
	v_exp_f32_e32 v100, v100
	v_mul_f32_e32 v101, 0xbfb8aa3b, v111
	v_exp_f32_e32 v101, v101
	v_cvt_pk_bf16_f32 v96, v96, v97
	v_add_f32_e32 v100, 1.0, v100
	v_rcp_f32_e32 v100, v100
	v_add_f32_e32 v101, 1.0, v101
	v_rcp_f32_e32 v101, v101
	v_mul_f32_e32 v97, v110, v102
	v_mul_f32_e32 v97, v97, v100
	v_mul_f32_e32 v100, v111, v103
	v_pk_mul_f32 v[104:105], v[104:105], v[116:117] op_sel_hi:[1,0]
	v_mul_f32_e32 v100, v100, v101
; __device__ __forceinline__ unsigned cvt_pk_bf16(float lo, float hi) { unsigned r; asm volatile("v_cvt_pk_bf16_f32 %0, %1, %2" : "=v"(r) : "v"(lo), "v"(hi)); return r; }
; __device__ __forceinline__ float silu_mul(float g, float u) { return g * u * __builtin_amdgcn_rcpf(1.0f + __builtin_amdgcn_exp2f(-1.4426950408889634f * g)); }
;     __device__ __forceinline__ void operator()(const f32x4 (&acc)[2][2][4][2], const Unit& u, int wr, int wc, int fr, int fq) const {
;     ...
;                 const f32x4 g0 = acc[ai][0][m][0] * rs, g1 = acc[ai][0][m][1] * rs, u0 = acc[ai][1][m][0] * rs, u1 = acc[ai][1][m][1] * rs;
;                 u32x4e w;
;                 w.x = cvt_pk_bf16(silu_mul(g0[0], u0[0]), silu_mul(g0[1], u0[1])); w.y = cvt_pk_bf16(silu_mul(g0[2], u0[2]), silu_mul(g0[3], u0[3]));
;                 w.z = cvt_pk_bf16(silu_mul(g1[0], u1[0]), silu_mul(g1[1], u1[1])); w.w = cvt_pk_bf16(silu_mul(g1[2], u1[2]), silu_mul(g1[3], u1[3]));
;                 *(u32x4e*)(O + (size_t)row * ldo + col0) = w;
	v_cvt_pk_bf16_f32 v97, v97, v100
	v_mul_f32_e32 v100, 0xbfb8aa3b, v104
	v_exp_f32_e32 v100, v100
	v_mul_f32_e32 v98, v104, v98
	v_pk_mul_f32 v[106:107], v[106:107], v[116:117] op_sel_hi:[1,0]
	v_mul_f32_e32 v99, v105, v99
	v_add_f32_e32 v100, 1.0, v100
	v_rcp_f32_e32 v100, v100
	v_mul_f32_e32 v101, 0xbfb8aa3b, v107
	v_exp_f32_e32 v101, v101
	v_mul_f32_e32 v98, v98, v100
	v_mul_f32_e32 v100, 0xbfb8aa3b, v105
	v_exp_f32_e32 v100, v100
	v_add_f32_e32 v101, 1.0, v101
	v_rcp_f32_e32 v101, v101
	v_add_f32_e32 v100, 1.0, v100
	v_rcp_f32_e32 v100, v100
	s_nop 0
	v_mul_f32_e32 v99, v99, v100
	v_mul_f32_e32 v100, 0xbfb8aa3b, v106
	v_exp_f32_e32 v100, v100
	v_cvt_pk_bf16_f32 v98, v98, v99
	v_mul_f32_e32 v99, v106, v118
	v_add_f32_e32 v100, 1.0, v100
	v_rcp_f32_e32 v100, v100
	s_nop 0
	v_mul_f32_e32 v99, v99, v100
	v_mul_f32_e32 v100, v107, v119
	v_mul_f32_e32 v100, v100, v101
	v_cvt_pk_bf16_f32 v99, v99, v100
	v_mad_i64_i32 v[100:101], s[10:11], v117, s24, v[112:113]
	v_lshl_add_u64 v[100:101], v[100:101], 0, v[114:115]
	global_store_dwordx4 v[100:101], v[96:99], off
	s_nop 1
	v_pk_mul_f32 v[96:97], v[82:83], v[142:143] op_sel_hi:[1,0]
	v_pk_mul_f32 v[82:83], v[80:81], v[142:143] op_sel_hi:[1,0]
	v_mul_f32_e32 v81, 0xbfb8aa3b, v92
	v_mul_f32_e32 v80, v92, v84
	v_exp_f32_e32 v81, v81
	v_mul_f32_e32 v84, 0xbfb8aa3b, v93
	v_exp_f32_e32 v84, v84
	v_mul_f32_e32 v82, v88, v82
	v_add_f32_e32 v81, 1.0, v81
	v_rcp_f32_e32 v81, v81
	v_add_f32_e32 v84, 1.0, v84
	v_rcp_f32_e32 v84, v84
	v_mul_f32_e32 v83, v89, v83
	v_mul_f32_e32 v80, v80, v81
	v_mul_f32_e32 v81, v93, v85
	v_mul_f32_e32 v81, v81, v84
	v_mul_f32_e32 v84, 0xbfb8aa3b, v94
	v_exp_f32_e32 v84, v84
	v_mul_f32_e32 v85, 0xbfb8aa3b, v95
	v_exp_f32_e32 v85, v85
	v_cvt_pk_bf16_f32 v80, v80, v81
	v_add_f32_e32 v84, 1.0, v84
	v_rcp_f32_e32 v84, v84
	v_add_f32_e32 v85, 1.0, v85
	v_rcp_f32_e32 v85, v85
	v_mul_f32_e32 v81, v94, v86
	v_mul_f32_e32 v81, v81, v84
	v_mul_f32_e32 v84, v95, v87
	v_mul_f32_e32 v84, v84, v85
	v_cvt_pk_bf16_f32 v81, v81, v84
	v_mul_f32_e32 v84, 0xbfb8aa3b, v88
	v_exp_f32_e32 v84, v84
	v_mul_f32_e32 v85, 0xbfb8aa3b, v91
	v_exp_f32_e32 v85, v85
	v_or_b32_e32 v98, 32, v153
	v_add_f32_e32 v84, 1.0, v84
	v_rcp_f32_e32 v84, v84
	v_add_f32_e32 v85, 1.0, v85
	v_rcp_f32_e32 v85, v85
	v_mul_f32_e32 v82, v82, v84
	v_mul_f32_e32 v84, 0xbfb8aa3b, v89
	v_exp_f32_e32 v84, v84
	s_nop 0
	v_add_f32_e32 v84, 1.0, v84
	v_rcp_f32_e32 v84, v84
	s_nop 0
	v_mul_f32_e32 v83, v83, v84
	v_mul_f32_e32 v84, 0xbfb8aa3b, v90
	v_exp_f32_e32 v84, v84
	v_cvt_pk_bf16_f32 v82, v82, v83
	v_mul_f32_e32 v83, v90, v96
	v_add_f32_e32 v84, 1.0, v84
	v_rcp_f32_e32 v84, v84
	s_nop 0
	v_mul_f32_e32 v83, v83, v84
	v_mul_f32_e32 v84, v91, v97
	v_mul_f32_e32 v84, v84, v85
	v_cvt_pk_bf16_f32 v83, v83, v84
	v_mad_i64_i32 v[84:85], s[10:11], v98, s24, v[112:113]
	v_lshl_add_u64 v[84:85], v[84:85], 0, v[114:115]
	global_store_dwordx4 v[84:85], v[80:83], off
	s_nop 1
	v_or_b32_e32 v81, 48, v153
	v_mov_b32_e32 v80, v143
	v_pk_mul_f32 v[76:77], v[76:77], v[80:81] op_sel_hi:[1,0]
	v_pk_mul_f32 v[68:69], v[68:69], v[80:81] op_sel_hi:[1,0]
	v_pk_mul_f32 v[82:83], v[66:67], v[80:81] op_sel_hi:[1,0]
	v_pk_mul_f32 v[66:67], v[64:65], v[80:81] op_sel_hi:[1,0]
	v_mul_f32_e32 v65, 0xbfb8aa3b, v76
	v_mul_f32_e32 v64, v76, v68
	v_exp_f32_e32 v65, v65
	v_mul_f32_e32 v68, 0xbfb8aa3b, v77
	v_exp_f32_e32 v68, v68
	v_pk_mul_f32 v[78:79], v[78:79], v[80:81] op_sel_hi:[1,0]
	v_add_f32_e32 v65, 1.0, v65
	v_rcp_f32_e32 v65, v65
	v_add_f32_e32 v68, 1.0, v68
	v_rcp_f32_e32 v68, v68
	v_pk_mul_f32 v[70:71], v[70:71], v[80:81] op_sel_hi:[1,0]
	v_mul_f32_e32 v64, v64, v65
	v_mul_f32_e32 v65, v77, v69
	v_mul_f32_e32 v65, v65, v68
	v_mul_f32_e32 v68, 0xbfb8aa3b, v78
	v_exp_f32_e32 v68, v68
	v_mul_f32_e32 v69, 0xbfb8aa3b, v79
	v_exp_f32_e32 v69, v69
	v_cvt_pk_bf16_f32 v64, v64, v65
	v_add_f32_e32 v68, 1.0, v68
	v_rcp_f32_e32 v68, v68
	v_add_f32_e32 v69, 1.0, v69
	v_rcp_f32_e32 v69, v69
	v_mul_f32_e32 v65, v78, v70
	v_mul_f32_e32 v65, v65, v68
	v_mul_f32_e32 v68, v79, v71
	v_pk_mul_f32 v[72:73], v[72:73], v[80:81] op_sel_hi:[1,0]
	v_mul_f32_e32 v68, v68, v69
	v_cvt_pk_bf16_f32 v65, v65, v68
	v_mul_f32_e32 v68, 0xbfb8aa3b, v72
	v_exp_f32_e32 v68, v68
	v_mul_f32_e32 v66, v72, v66
	v_pk_mul_f32 v[74:75], v[74:75], v[80:81] op_sel_hi:[1,0]
	v_mul_f32_e32 v67, v73, v67
	v_add_f32_e32 v68, 1.0, v68
	v_rcp_f32_e32 v68, v68
	v_mul_f32_e32 v69, 0xbfb8aa3b, v75
	v_exp_f32_e32 v69, v69
	v_mul_f32_e32 v66, v66, v68
	v_mul_f32_e32 v68, 0xbfb8aa3b, v73
	v_exp_f32_e32 v68, v68
	v_add_f32_e32 v69, 1.0, v69
	v_rcp_f32_e32 v69, v69
	v_add_f32_e32 v68, 1.0, v68
	v_rcp_f32_e32 v68, v68
	s_nop 0
	v_mul_f32_e32 v67, v67, v68
	v_mul_f32_e32 v68, 0xbfb8aa3b, v74
	v_exp_f32_e32 v68, v68
	v_cvt_pk_bf16_f32 v66, v66, v67
	v_mul_f32_e32 v67, v74, v82
	v_add_f32_e32 v68, 1.0, v68
	v_rcp_f32_e32 v68, v68
	s_nop 0
	v_mul_f32_e32 v67, v67, v68
	v_mul_f32_e32 v68, v75, v83
	v_mul_f32_e32 v68, v68, v69
	v_cvt_pk_bf16_f32 v67, v67, v68
	v_mad_i64_i32 v[68:69], s[10:11], v81, s24, v[112:113]
	v_lshl_add_u64 v[68:69], v[68:69], 0, v[114:115]
	global_store_dwordx4 v[68:69], v[64:67], off
	s_nop 1
	v_pk_mul_f32 v[64:65], v[50:51], v[140:141] op_sel_hi:[1,0]
	v_pk_mul_f32 v[50:51], v[48:49], v[140:141] op_sel_hi:[1,0]
	v_mul_f32_e32 v49, 0xbfb8aa3b, v60
	v_mul_f32_e32 v48, v60, v52
	v_exp_f32_e32 v49, v49
	v_mul_f32_e32 v52, 0xbfb8aa3b, v61
	v_exp_f32_e32 v52, v52
	v_mul_f32_e32 v50, v56, v50
	v_add_f32_e32 v49, 1.0, v49
	v_rcp_f32_e32 v49, v49
	v_add_f32_e32 v52, 1.0, v52
	v_rcp_f32_e32 v52, v52
	v_mul_f32_e32 v51, v57, v51
	v_mul_f32_e32 v48, v48, v49
	v_mul_f32_e32 v49, v61, v53
	v_mul_f32_e32 v49, v49, v52
; __device__ __forceinline__ unsigned cvt_pk_bf16(float lo, float hi) { unsigned r; asm volatile("v_cvt_pk_bf16_f32 %0, %1, %2" : "=v"(r) : "v"(lo), "v"(hi)); return r; }
; __device__ __forceinline__ float silu_mul(float g, float u) { return g * u * __builtin_amdgcn_rcpf(1.0f + __builtin_amdgcn_exp2f(-1.4426950408889634f * g)); }
;     __device__ __forceinline__ void operator()(const f32x4 (&acc)[2][2][4][2], const Unit& u, int wr, int wc, int fr, int fq) const {
;     ...
;                 const f32x4 g0 = acc[ai][0][m][0] * rs, g1 = acc[ai][0][m][1] * rs, u0 = acc[ai][1][m][0] * rs, u1 = acc[ai][1][m][1] * rs;
;                 u32x4e w;
;                 w.x = cvt_pk_bf16(silu_mul(g0[0], u0[0]), silu_mul(g0[1], u0[1])); w.y = cvt_pk_bf16(silu_mul(g0[2], u0[2]), silu_mul(g0[3], u0[3]));
;                 w.z = cvt_pk_bf16(silu_mul(g1[0], u1[0]), silu_mul(g1[1], u1[1])); w.w = cvt_pk_bf16(silu_mul(g1[2], u1[2]), silu_mul(g1[3], u1[3]));
;                 *(u32x4e*)(O + (size_t)row * ldo + col0) = w;
	v_mul_f32_e32 v52, 0xbfb8aa3b, v62
	v_exp_f32_e32 v52, v52
	v_mul_f32_e32 v53, 0xbfb8aa3b, v63
	v_exp_f32_e32 v53, v53
	v_cvt_pk_bf16_f32 v48, v48, v49
	v_add_f32_e32 v52, 1.0, v52
	v_rcp_f32_e32 v52, v52
	v_add_f32_e32 v53, 1.0, v53
	v_rcp_f32_e32 v53, v53
	v_mul_f32_e32 v49, v62, v54
	v_mul_f32_e32 v49, v49, v52
	v_mul_f32_e32 v52, v63, v55
	v_mul_f32_e32 v52, v52, v53
	v_cvt_pk_bf16_f32 v49, v49, v52
	v_mul_f32_e32 v52, 0xbfb8aa3b, v56
	v_exp_f32_e32 v52, v52
	v_mul_f32_e32 v53, 0xbfb8aa3b, v59
	v_exp_f32_e32 v53, v53
	v_add_u32_e32 v66, 0x80, v153
	v_add_f32_e32 v52, 1.0, v52
	v_rcp_f32_e32 v52, v52
	v_add_f32_e32 v53, 1.0, v53
	v_rcp_f32_e32 v53, v53
	v_mul_f32_e32 v50, v50, v52
	v_mul_f32_e32 v52, 0xbfb8aa3b, v57
	v_exp_f32_e32 v52, v52
	s_nop 0
	v_add_f32_e32 v52, 1.0, v52
	v_rcp_f32_e32 v52, v52
	s_nop 0
	v_mul_f32_e32 v51, v51, v52
	v_mul_f32_e32 v52, 0xbfb8aa3b, v58
	v_exp_f32_e32 v52, v52
	v_cvt_pk_bf16_f32 v50, v50, v51
	v_mul_f32_e32 v51, v58, v64
	v_add_f32_e32 v52, 1.0, v52
	v_rcp_f32_e32 v52, v52
	s_nop 0
	v_mul_f32_e32 v51, v51, v52
	v_mul_f32_e32 v52, v59, v65
	v_mul_f32_e32 v52, v52, v53
	v_cvt_pk_bf16_f32 v51, v51, v52
	v_mad_i64_i32 v[52:53], s[10:11], v66, s24, v[112:113]
	v_lshl_add_u64 v[52:53], v[52:53], 0, v[114:115]
	global_store_dwordx4 v[52:53], v[48:51], off
	s_nop 1
	v_add_u32_e32 v49, 0x90, v153
	v_mov_b32_e32 v48, v141
	v_pk_mul_f32 v[44:45], v[44:45], v[48:49] op_sel_hi:[1,0]
	v_pk_mul_f32 v[36:37], v[36:37], v[48:49] op_sel_hi:[1,0]
	v_pk_mul_f32 v[50:51], v[34:35], v[48:49] op_sel_hi:[1,0]
	v_pk_mul_f32 v[34:35], v[32:33], v[48:49] op_sel_hi:[1,0]
	v_mul_f32_e32 v33, 0xbfb8aa3b, v44
	v_mul_f32_e32 v32, v44, v36
	v_exp_f32_e32 v33, v33
	v_mul_f32_e32 v36, 0xbfb8aa3b, v45
	v_exp_f32_e32 v36, v36
	v_pk_mul_f32 v[46:47], v[46:47], v[48:49] op_sel_hi:[1,0]
	v_add_f32_e32 v33, 1.0, v33
	v_rcp_f32_e32 v33, v33
	v_add_f32_e32 v36, 1.0, v36
	v_rcp_f32_e32 v36, v36
	v_pk_mul_f32 v[38:39], v[38:39], v[48:49] op_sel_hi:[1,0]
	v_mul_f32_e32 v32, v32, v33
	v_mul_f32_e32 v33, v45, v37
	v_mul_f32_e32 v33, v33, v36
	v_mul_f32_e32 v36, 0xbfb8aa3b, v46
	v_exp_f32_e32 v36, v36
	v_mul_f32_e32 v37, 0xbfb8aa3b, v47
	v_exp_f32_e32 v37, v37
	v_cvt_pk_bf16_f32 v32, v32, v33
	v_add_f32_e32 v36, 1.0, v36
	v_rcp_f32_e32 v36, v36
	v_add_f32_e32 v37, 1.0, v37
	v_rcp_f32_e32 v37, v37
	v_mul_f32_e32 v33, v46, v38
	v_mul_f32_e32 v33, v33, v36
	v_mul_f32_e32 v36, v47, v39
	v_pk_mul_f32 v[40:41], v[40:41], v[48:49] op_sel_hi:[1,0]
	v_mul_f32_e32 v36, v36, v37
	v_cvt_pk_bf16_f32 v33, v33, v36
	v_mul_f32_e32 v36, 0xbfb8aa3b, v40
	v_exp_f32_e32 v36, v36
	v_mul_f32_e32 v34, v40, v34
	v_pk_mul_f32 v[42:43], v[42:43], v[48:49] op_sel_hi:[1,0]
	v_mul_f32_e32 v35, v41, v35
	v_add_f32_e32 v36, 1.0, v36
	v_rcp_f32_e32 v36, v36
	v_mul_f32_e32 v37, 0xbfb8aa3b, v43
	v_exp_f32_e32 v37, v37
	v_mul_f32_e32 v34, v34, v36
	v_mul_f32_e32 v36, 0xbfb8aa3b, v41
	v_exp_f32_e32 v36, v36
	v_add_f32_e32 v37, 1.0, v37
	v_rcp_f32_e32 v37, v37
	v_add_f32_e32 v36, 1.0, v36
	v_rcp_f32_e32 v36, v36
	s_nop 0
	v_mul_f32_e32 v35, v35, v36
	v_mul_f32_e32 v36, 0xbfb8aa3b, v42
	v_exp_f32_e32 v36, v36
	v_cvt_pk_bf16_f32 v34, v34, v35
	v_mul_f32_e32 v35, v42, v50
	v_add_f32_e32 v36, 1.0, v36
	v_rcp_f32_e32 v36, v36
	s_nop 0
	v_mul_f32_e32 v35, v35, v36
	v_mul_f32_e32 v36, v43, v51
	v_mul_f32_e32 v36, v36, v37
	v_cvt_pk_bf16_f32 v35, v35, v36
	v_mad_i64_i32 v[36:37], s[10:11], v49, s24, v[112:113]
	v_lshl_add_u64 v[36:37], v[36:37], 0, v[114:115]
	global_store_dwordx4 v[36:37], v[32:35], off
	s_nop 1
	v_pk_mul_f32 v[32:33], v[18:19], v[138:139] op_sel_hi:[1,0]
	v_pk_mul_f32 v[18:19], v[16:17], v[138:139] op_sel_hi:[1,0]
	v_mul_f32_e32 v17, 0xbfb8aa3b, v28
	v_mul_f32_e32 v16, v28, v20
	v_exp_f32_e32 v17, v17
	v_mul_f32_e32 v20, 0xbfb8aa3b, v29
	v_exp_f32_e32 v20, v20
	v_mul_f32_e32 v18, v24, v18
	v_add_f32_e32 v17, 1.0, v17
	v_rcp_f32_e32 v17, v17
	v_add_f32_e32 v20, 1.0, v20
	v_rcp_f32_e32 v20, v20
	v_mul_f32_e32 v19, v25, v19
	v_mul_f32_e32 v16, v16, v17
	v_mul_f32_e32 v17, v29, v21
	v_mul_f32_e32 v17, v17, v20
	v_mul_f32_e32 v20, 0xbfb8aa3b, v30
	v_exp_f32_e32 v20, v20
	v_mul_f32_e32 v21, 0xbfb8aa3b, v31
	v_exp_f32_e32 v21, v21
	v_cvt_pk_bf16_f32 v16, v16, v17
	v_add_f32_e32 v20, 1.0, v20
	v_rcp_f32_e32 v20, v20
	v_add_f32_e32 v21, 1.0, v21
	v_rcp_f32_e32 v21, v21
	v_mul_f32_e32 v17, v30, v22
	v_mul_f32_e32 v17, v17, v20
	v_mul_f32_e32 v20, v31, v23
	v_mul_f32_e32 v20, v20, v21
	v_cvt_pk_bf16_f32 v17, v17, v20
	v_mul_f32_e32 v20, 0xbfb8aa3b, v24
	v_exp_f32_e32 v20, v20
	v_mul_f32_e32 v21, 0xbfb8aa3b, v27
	v_exp_f32_e32 v21, v21
	v_add_u32_e32 v34, 0xa0, v153
	v_add_f32_e32 v20, 1.0, v20
	v_rcp_f32_e32 v20, v20
	v_add_f32_e32 v21, 1.0, v21
	v_rcp_f32_e32 v21, v21
	v_mul_f32_e32 v18, v18, v20
	v_mul_f32_e32 v20, 0xbfb8aa3b, v25
	v_exp_f32_e32 v20, v20
	s_nop 0
	v_add_f32_e32 v20, 1.0, v20
	v_rcp_f32_e32 v20, v20
	s_nop 0
	v_mul_f32_e32 v19, v19, v20
	v_mul_f32_e32 v20, 0xbfb8aa3b, v26
	v_exp_f32_e32 v20, v20
	v_cvt_pk_bf16_f32 v18, v18, v19
	v_mul_f32_e32 v19, v26, v32
	v_add_f32_e32 v20, 1.0, v20
	v_rcp_f32_e32 v20, v20
	s_nop 0
	v_mul_f32_e32 v19, v19, v20
	v_mul_f32_e32 v20, v27, v33
	v_mul_f32_e32 v20, v20, v21
	v_cvt_pk_bf16_f32 v19, v19, v20
	v_mad_i64_i32 v[20:21], s[10:11], v34, s24, v[112:113]
	v_lshl_add_u64 v[20:21], v[20:21], 0, v[114:115]
	global_store_dwordx4 v[20:21], v[16:19], off
	s_nop 1
	v_add_u32_e32 v17, 0xb0, v153
	v_mov_b32_e32 v16, v139
	v_pk_mul_f32 v[12:13], v[12:13], v[16:17] op_sel_hi:[1,0]
	v_pk_mul_f32 v[4:5], v[4:5], v[16:17] op_sel_hi:[1,0]
	v_pk_mul_f32 v[18:19], v[2:3], v[16:17] op_sel_hi:[1,0]
	v_pk_mul_f32 v[2:3], v[0:1], v[16:17] op_sel_hi:[1,0]
; __device__ __forceinline__ unsigned cvt_pk_bf16(float lo, float hi) { unsigned r; asm volatile("v_cvt_pk_bf16_f32 %0, %1, %2" : "=v"(r) : "v"(lo), "v"(hi)); return r; }
; __device__ __forceinline__ float silu_mul(float g, float u) { return g * u * __builtin_amdgcn_rcpf(1.0f + __builtin_amdgcn_exp2f(-1.4426950408889634f * g)); }
; #define PG8_STAGE(bufoff, gbase, voff) do { _Pragma("unroll") for (int _i = 0; _i < 2; ++_i) \
;         __builtin_amdgcn_global_load_lds((const unsigned*)((const char*)(gbase) + (voff)[_i]), (PG8_LAS unsigned*)(lds + (bufoff) + ldsw + _i * 8192), 16, 0, 0); } while (0)
; #define PG8_LDA(dst, b, h) do { _Pragma("unroll") for (int m = 0; m < 4; ++m) _Pragma("unroll") for (int k = 0; k < 2; ++k) dst[m][k] = *(const PG8_LAS bf16x8*)(lds + PG8_SA(b, h) + aoff + m * 2048 + k * 1024); } while (0)
; #define PG8_LDB(dst, b, h) do { _Pragma("unroll") for (int n = 0; n < 2; ++n) _Pragma("unroll") for (int k = 0; k < 2; ++k) dst[n][k] = *(const PG8_LAS bf16x8*)(lds + PG8_SB(b, h) + boff + n * 2048 + k * 1024); } while (0)
; #define PG8_WAIT_V(n) asm volatile("s_waitcnt vmcnt(" #n ")" ::: "memory")
; #define PG8_WAIT_L(n) asm volatile("s_waitcnt lgkmcnt(" #n ")" ::: "memory")
; #define PG8_BAR __builtin_amdgcn_s_barrier()
;     __device__ __forceinline__ void operator()(const f32x4 (&acc)[2][2][4][2], const Unit& u, int wr, int wc, int fr, int fq) const {
;     ...
;                 const f32x4 g0 = acc[ai][0][m][0] * rs, g1 = acc[ai][0][m][1] * rs, u0 = acc[ai][1][m][0] * rs, u1 = acc[ai][1][m][1] * rs;
;                 u32x4e w;
;                 w.x = cvt_pk_bf16(silu_mul(g0[0], u0[0]), silu_mul(g0[1], u0[1])); w.y = cvt_pk_bf16(silu_mul(g0[2], u0[2]), silu_mul(g0[3], u0[3]));
;                 w.z = cvt_pk_bf16(silu_mul(g1[0], u1[0]), silu_mul(g1[1], u1[1])); w.w = cvt_pk_bf16(silu_mul(g1[2], u1[2]), silu_mul(g1[3], u1[3]));
;                 *(u32x4e*)(O + (size_t)row * ldo + col0) = w;
; template <class Epi, class Sched, bool ALIGN_EPI = false, bool SP2 = false>
; __device__ __forceinline__ void gemm_phase(PG8_LAS unsigned char* lds, const Gemm g, const Sched& S, const Epi& E) {
;     ...
;             PG8_LDB(B0, 0, 0); PG8_LDB(B1, 0, 1); PG8_SCHED; PG8_LDA(At, 0, 0); PG8_STAGE(PG8_SA(1, 1), a1 + hstep, voffA);
;             PG8_WAIT_V(8); PG8_WAIT_L(0); PG8_BAR; PG8_MMA(0, 0, At, B0); PG8_MMA(0, 1, At, B1); PG8_BAR; PG8_SCHED;
	v_mul_f32_e32 v1, 0xbfb8aa3b, v12
	v_mul_f32_e32 v0, v12, v4
	v_exp_f32_e32 v1, v1
	v_mul_f32_e32 v4, 0xbfb8aa3b, v13
	v_exp_f32_e32 v4, v4
	v_pk_mul_f32 v[14:15], v[14:15], v[16:17] op_sel_hi:[1,0]
	v_add_f32_e32 v1, 1.0, v1
	v_rcp_f32_e32 v1, v1
	v_add_f32_e32 v4, 1.0, v4
	v_rcp_f32_e32 v4, v4
	v_pk_mul_f32 v[6:7], v[6:7], v[16:17] op_sel_hi:[1,0]
	v_mul_f32_e32 v0, v0, v1
	v_mul_f32_e32 v1, v13, v5
	v_mul_f32_e32 v1, v1, v4
	v_mul_f32_e32 v4, 0xbfb8aa3b, v14
	v_exp_f32_e32 v4, v4
	v_mul_f32_e32 v5, 0xbfb8aa3b, v15
	v_exp_f32_e32 v5, v5
	v_cvt_pk_bf16_f32 v0, v0, v1
	v_add_f32_e32 v4, 1.0, v4
	v_rcp_f32_e32 v4, v4
	v_add_f32_e32 v5, 1.0, v5
	v_rcp_f32_e32 v5, v5
	v_mul_f32_e32 v1, v14, v6
	v_mul_f32_e32 v1, v1, v4
	v_mul_f32_e32 v4, v15, v7
	v_pk_mul_f32 v[8:9], v[8:9], v[16:17] op_sel_hi:[1,0]
	v_mul_f32_e32 v4, v4, v5
	v_cvt_pk_bf16_f32 v1, v1, v4
	v_mul_f32_e32 v4, 0xbfb8aa3b, v8
	v_exp_f32_e32 v4, v4
	v_mul_f32_e32 v2, v8, v2
	v_pk_mul_f32 v[10:11], v[10:11], v[16:17] op_sel_hi:[1,0]
	v_mul_f32_e32 v3, v9, v3
	v_add_f32_e32 v4, 1.0, v4
	v_rcp_f32_e32 v4, v4
	v_mul_f32_e32 v5, 0xbfb8aa3b, v11
	v_exp_f32_e32 v5, v5
	v_mul_f32_e32 v2, v2, v4
	v_mul_f32_e32 v4, 0xbfb8aa3b, v9
	v_exp_f32_e32 v4, v4
	v_add_f32_e32 v5, 1.0, v5
	v_rcp_f32_e32 v5, v5
	v_add_f32_e32 v4, 1.0, v4
	v_rcp_f32_e32 v4, v4
	s_nop 0
	v_mul_f32_e32 v3, v3, v4
	v_mul_f32_e32 v4, 0xbfb8aa3b, v10
	v_exp_f32_e32 v4, v4
	v_cvt_pk_bf16_f32 v2, v2, v3
	v_mul_f32_e32 v3, v10, v18
	v_add_f32_e32 v4, 1.0, v4
	v_rcp_f32_e32 v4, v4
	s_nop 0
	v_mul_f32_e32 v3, v3, v4
	v_mul_f32_e32 v4, v11, v19
	v_mul_f32_e32 v4, v4, v5
	v_cvt_pk_bf16_f32 v3, v3, v4
	v_mad_i64_i32 v[4:5], s[10:11], v17, s24, v[112:113]
	v_lshl_add_u64 v[4:5], v[4:5], 0, v[114:115]
	s_mov_b64 s[10:11], -1
	global_store_dwordx4 v[4:5], v[0:3], off
	s_cbranch_vccnz .LBB0_395
	s_andn2_b64 vcc, exec, s[4:5]
	s_cbranch_vccnz .LBB0_394
	s_barrier
	s_branch .LBB0_394
.Lpeel_act:
	s_add_u32 s12, s10, 0xfffc0080
	s_addc_u32 s13, s11, -1
	s_add_i32 s51, 0, 0x10000
	s_cmp_eq_u32 s50, 12
	s_cselect_b32 s15, s41, s13
	s_cselect_b32 s14, s46, s12
	v_add_u32_e32 v146, s51, v149
	s_cselect_b32 s13, s9, s49
	s_cselect_b32 s12, s47, s48
	s_add_i32 s54, 0, 0x14000
	ds_read_b128 v[138:141], v146
	ds_read_b128 v[142:145], v146 offset:1024
	ds_read_b128 v[168:171], v146 offset:2048
	ds_read_b128 v[172:175], v146 offset:3072
	v_add_u32_e32 v146, s54, v149
	ds_read_b128 v[176:179], v146
	ds_read_b128 v[180:183], v146 offset:1024
	ds_read_b128 v[184:187], v146 offset:2048
	ds_read_b128 v[188:191], v146 offset:3072
	ds_read_b128 v[192:195], v152
	ds_read_b128 v[196:199], v152 offset:1024
	ds_read_b128 v[200:203], v152 offset:2048
	ds_read_b128 v[204:207], v152 offset:3072
	ds_read_b128 v[208:211], v152 offset:4096
	ds_read_b128 v[212:215], v152 offset:5120
	ds_read_b128 v[216:219], v152 offset:6144
	ds_read_b128 v[220:223], v152 offset:7168
	s_waitcnt vmcnt(16)
	s_waitcnt lgkmcnt(0)
	s_barrier
	s_waitcnt lgkmcnt(0)
	v_mfma_f32_16x16x32_bf16 v[124:127], v[138:141], v[192:195], v[124:127]
	v_mfma_f32_16x16x32_bf16 v[120:123], v[168:171], v[192:195], v[120:123]
	v_mfma_f32_16x16x32_bf16 v[108:111], v[138:141], v[200:203], v[108:111]
	v_mfma_f32_16x16x32_bf16 v[104:107], v[168:171], v[200:203], v[104:107]
	v_mfma_f32_16x16x32_bf16 v[92:95], v[138:141], v[208:211], v[92:95]
	v_mfma_f32_16x16x32_bf16 v[88:91], v[168:171], v[208:211], v[88:91]
	v_mfma_f32_16x16x32_bf16 v[76:79], v[138:141], v[216:219], v[76:79]
	v_mfma_f32_16x16x32_bf16 v[72:75], v[168:171], v[216:219], v[72:75]
	v_mfma_f32_16x16x32_bf16 v[124:127], v[142:145], v[196:199], v[124:127]
	v_mfma_f32_16x16x32_bf16 v[120:123], v[172:175], v[196:199], v[120:123]
	v_mfma_f32_16x16x32_bf16 v[108:111], v[142:145], v[204:207], v[108:111]
	v_mfma_f32_16x16x32_bf16 v[104:107], v[172:175], v[204:207], v[104:107]
	v_mfma_f32_16x16x32_bf16 v[92:95], v[142:145], v[212:215], v[92:95]
	v_mfma_f32_16x16x32_bf16 v[88:91], v[172:175], v[212:215], v[88:91]
	v_mfma_f32_16x16x32_bf16 v[76:79], v[142:145], v[220:223], v[76:79]
	v_mfma_f32_16x16x32_bf16 v[72:75], v[172:175], v[220:223], v[72:75]
	v_mfma_f32_16x16x32_bf16 v[116:119], v[176:179], v[192:195], v[116:119]
	v_mfma_f32_16x16x32_bf16 v[112:115], v[184:187], v[192:195], v[112:115]
	v_mfma_f32_16x16x32_bf16 v[100:103], v[176:179], v[200:203], v[100:103]
	v_mfma_f32_16x16x32_bf16 v[96:99], v[184:187], v[200:203], v[96:99]
	v_mfma_f32_16x16x32_bf16 v[84:87], v[176:179], v[208:211], v[84:87]
	v_mfma_f32_16x16x32_bf16 v[80:83], v[184:187], v[208:211], v[80:83]
	v_mfma_f32_16x16x32_bf16 v[68:71], v[176:179], v[216:219], v[68:71]
	v_mfma_f32_16x16x32_bf16 v[64:67], v[184:187], v[216:219], v[64:67]
	v_mfma_f32_16x16x32_bf16 v[116:119], v[180:183], v[196:199], v[116:119]
	v_mfma_f32_16x16x32_bf16 v[112:115], v[188:191], v[196:199], v[112:115]
	v_mfma_f32_16x16x32_bf16 v[100:103], v[180:183], v[204:207], v[100:103]
	v_mfma_f32_16x16x32_bf16 v[96:99], v[188:191], v[204:207], v[96:99]
	v_mfma_f32_16x16x32_bf16 v[84:87], v[180:183], v[212:215], v[84:87]
	v_mfma_f32_16x16x32_bf16 v[80:83], v[188:191], v[212:215], v[80:83]
	v_mfma_f32_16x16x32_bf16 v[68:71], v[180:183], v[220:223], v[68:71]
	v_mfma_f32_16x16x32_bf16 v[64:67], v[188:191], v[220:223], v[64:67]
	s_barrier
; #define PG8_STAGE(bufoff, gbase, voff) do { _Pragma("unroll") for (int _i = 0; _i < 2; ++_i) \
;         __builtin_amdgcn_global_load_lds((const unsigned*)((const char*)(gbase) + (voff)[_i]), (PG8_LAS unsigned*)(lds + (bufoff) + ldsw + _i * 8192), 16, 0, 0); } while (0)
; #define PG8_LDA(dst, b, h) do { _Pragma("unroll") for (int m = 0; m < 4; ++m) _Pragma("unroll") for (int k = 0; k < 2; ++k) dst[m][k] = *(const PG8_LAS bf16x8*)(lds + PG8_SA(b, h) + aoff + m * 2048 + k * 1024); } while (0)
; #define PG8_LDB(dst, b, h) do { _Pragma("unroll") for (int n = 0; n < 2; ++n) _Pragma("unroll") for (int k = 0; k < 2; ++k) dst[n][k] = *(const PG8_LAS bf16x8*)(lds + PG8_SB(b, h) + boff + n * 2048 + k * 1024); } while (0)
; #define PG8_MMA(ai, bj, At, Bt) do { __builtin_amdgcn_s_setprio(1); _Pragma("unroll") for (int m = 0; m < 4; ++m) _Pragma("unroll") for (int n = 0; n < 2; ++n) _Pragma("unroll") for (int k = 0; k < 2; ++k) \
;         acc[ai][bj][m][n] = __builtin_amdgcn_mfma_f32_16x16x32_bf16(Bt[n][k], At[m][k], acc[ai][bj][m][n], 0, 0, 0); __builtin_amdgcn_s_setprio(0); } while (0)
; #define PG8_WAIT_V(n) asm volatile("s_waitcnt vmcnt(" #n ")" ::: "memory")
; #define PG8_WAIT_L(n) asm volatile("s_waitcnt lgkmcnt(" #n ")" ::: "memory")
; #define PG8_BAR __builtin_amdgcn_s_barrier()
; #define PG8_SCHED __builtin_amdgcn_sched_barrier(0)
; template <class Epi, class Sched, bool ALIGN_EPI = false, bool SP2 = false>
; __device__ __forceinline__ void gemm_phase(PG8_LAS unsigned char* lds, const Gemm g, const Sched& S, const Epi& E) {
;     ...
;             PG8_LDA(At, 0, 1); PG8_STAGE(PG8_SB(0, 0), b2, voffB); PG8_STAGE(PG8_SB(0, 1), b2 + hstep, voffB); PG8_STAGE(PG8_SA(0, 0), a2, voffA);
;             PG8_WAIT_V(8); PG8_WAIT_L(0); PG8_BAR; PG8_MMA(1, 0, At, B0); PG8_MMA(1, 1, At, B1); PG8_BAR; PG8_SCHED;
;             PG8_LDB(B0, 1, 0); PG8_LDB(B1, 1, 1); PG8_SCHED; PG8_LDA(At, 1, 0); PG8_STAGE(PG8_SA(0, 1), a2 + hstep, voffA);
;             PG8_WAIT_V(8); PG8_WAIT_L(0); PG8_BAR; PG8_MMA(0, 0, At, B0); PG8_MMA(0, 1, At, B1); PG8_BAR; PG8_SCHED;
	s_add_i32 s51, s51, s21
	v_lshl_add_u64 v[146:147], s[12:13], 0, v[156:157]
	s_mov_b32 m0, s51
	ds_read_b128 v[192:195], v152 offset:16384
	ds_read_b128 v[196:199], v152 offset:17408
	ds_read_b128 v[200:203], v152 offset:18432
	ds_read_b128 v[204:207], v152 offset:19456
	ds_read_b128 v[208:211], v152 offset:20480
	ds_read_b128 v[212:215], v152 offset:21504
	ds_read_b128 v[216:219], v152 offset:22528
	ds_read_b128 v[220:223], v152 offset:23552
	global_load_lds_dwordx4 v[146:147], off
	s_add_i32 m0, s51, 0x2000
	s_add_u32 s52, s12, 0x40000
	v_lshl_add_u64 v[154:155], s[12:13], 0, v[128:129]
	s_addc_u32 s53, s13, 0
	s_add_i32 s51, s54, s21
	global_load_lds_dwordx4 v[154:155], off
	v_lshl_add_u64 v[224:225], s[52:53], 0, v[156:157]
	s_mov_b32 m0, s51
	v_lshl_add_u64 v[226:227], s[14:15], 0, v[130:131]
	global_load_lds_dwordx4 v[224:225], off
	v_lshl_add_u64 v[224:225], s[52:53], 0, v[128:129]
	s_add_i32 m0, s51, 0x2000
	s_nop 0
	global_load_lds_dwordx4 v[224:225], off
	v_lshl_add_u64 v[224:225], s[14:15], 0, v[132:133]
	s_mov_b32 m0, s25
	s_nop 0
	global_load_lds_dwordx4 v[224:225], off
	s_mov_b32 m0, s26
	s_nop 0
	global_load_lds_dwordx4 v[226:227], off
	s_waitcnt vmcnt(16)
	s_waitcnt lgkmcnt(0)
	s_barrier
	s_waitcnt lgkmcnt(0)
	v_mfma_f32_16x16x32_bf16 v[60:63], v[138:141], v[192:195], v[60:63]
	v_mfma_f32_16x16x32_bf16 v[56:59], v[168:171], v[192:195], v[56:59]
	v_mfma_f32_16x16x32_bf16 v[44:47], v[138:141], v[200:203], v[44:47]
	v_mfma_f32_16x16x32_bf16 v[40:43], v[168:171], v[200:203], v[40:43]
	v_mfma_f32_16x16x32_bf16 v[28:31], v[138:141], v[208:211], v[28:31]
	v_mfma_f32_16x16x32_bf16 v[24:27], v[168:171], v[208:211], v[24:27]
	v_mfma_f32_16x16x32_bf16 v[12:15], v[138:141], v[216:219], v[12:15]
	v_mfma_f32_16x16x32_bf16 v[8:11], v[168:171], v[216:219], v[8:11]
	v_mfma_f32_16x16x32_bf16 v[60:63], v[142:145], v[196:199], v[60:63]
	v_mfma_f32_16x16x32_bf16 v[56:59], v[172:175], v[196:199], v[56:59]
	v_mfma_f32_16x16x32_bf16 v[44:47], v[142:145], v[204:207], v[44:47]
	v_mfma_f32_16x16x32_bf16 v[40:43], v[172:175], v[204:207], v[40:43]
	v_mfma_f32_16x16x32_bf16 v[28:31], v[142:145], v[212:215], v[28:31]
	v_mfma_f32_16x16x32_bf16 v[24:27], v[172:175], v[212:215], v[24:27]
	v_mfma_f32_16x16x32_bf16 v[12:15], v[142:145], v[220:223], v[12:15]
	v_mfma_f32_16x16x32_bf16 v[8:11], v[172:175], v[220:223], v[8:11]
	v_mfma_f32_16x16x32_bf16 v[52:55], v[176:179], v[192:195], v[52:55]
	v_mfma_f32_16x16x32_bf16 v[48:51], v[184:187], v[192:195], v[48:51]
	v_mfma_f32_16x16x32_bf16 v[36:39], v[176:179], v[200:203], v[36:39]
	v_mfma_f32_16x16x32_bf16 v[32:35], v[184:187], v[200:203], v[32:35]
	v_mfma_f32_16x16x32_bf16 v[20:23], v[176:179], v[208:211], v[20:23]
	v_mfma_f32_16x16x32_bf16 v[16:19], v[184:187], v[208:211], v[16:19]
	v_mfma_f32_16x16x32_bf16 v[4:7], v[176:179], v[216:219], v[4:7]
	v_mfma_f32_16x16x32_bf16 v[0:3], v[184:187], v[216:219], v[0:3]
	v_mfma_f32_16x16x32_bf16 v[52:55], v[180:183], v[196:199], v[52:55]
	v_mfma_f32_16x16x32_bf16 v[48:51], v[188:191], v[196:199], v[48:51]
	v_mfma_f32_16x16x32_bf16 v[36:39], v[180:183], v[204:207], v[36:39]
	v_mfma_f32_16x16x32_bf16 v[32:35], v[188:191], v[204:207], v[32:35]
	v_mfma_f32_16x16x32_bf16 v[20:23], v[180:183], v[212:215], v[20:23]
	v_mfma_f32_16x16x32_bf16 v[16:19], v[188:191], v[212:215], v[16:19]
	v_mfma_f32_16x16x32_bf16 v[4:7], v[180:183], v[220:223], v[4:7]
	v_mfma_f32_16x16x32_bf16 v[0:3], v[188:191], v[220:223], v[0:3]
	s_barrier
	s_add_i32 s51, 0, 0x18000
	v_add_u32_e32 v153, s51, v149
	s_add_i32 s52, 0, 0x1c000
	ds_read_b128 v[138:141], v153
	ds_read_b128 v[142:145], v153 offset:1024
	ds_read_b128 v[168:171], v153 offset:2048
	ds_read_b128 v[172:175], v153 offset:3072
	v_add_u32_e32 v153, s52, v149
	ds_read_b128 v[176:179], v153
	ds_read_b128 v[180:183], v153 offset:1024
	ds_read_b128 v[184:187], v153 offset:2048
	ds_read_b128 v[188:191], v153 offset:3072
	s_add_u32 s14, s14, 0x40000
	s_addc_u32 s15, s15, 0
	s_mov_b32 m0, s27
	v_lshl_add_u64 v[228:229], s[14:15], 0, v[132:133]
	ds_read_b128 v[192:195], v152 offset:32768
	ds_read_b128 v[196:199], v152 offset:33792
	ds_read_b128 v[200:203], v152 offset:34816
	ds_read_b128 v[204:207], v152 offset:35840
	ds_read_b128 v[208:211], v152 offset:36864
	ds_read_b128 v[212:215], v152 offset:37888
	ds_read_b128 v[216:219], v152 offset:38912
	ds_read_b128 v[220:223], v152 offset:39936
	global_load_lds_dwordx4 v[228:229], off
	v_lshl_add_u64 v[228:229], s[14:15], 0, v[130:131]
	s_mov_b32 m0, s28
	s_nop 0
	global_load_lds_dwordx4 v[228:229], off
	s_waitcnt vmcnt(16)
	s_waitcnt lgkmcnt(0)
	s_barrier
; #define PG8_STAGE(bufoff, gbase, voff) do { _Pragma("unroll") for (int _i = 0; _i < 2; ++_i) \
;         __builtin_amdgcn_global_load_lds((const unsigned*)((const char*)(gbase) + (voff)[_i]), (PG8_LAS unsigned*)(lds + (bufoff) + ldsw + _i * 8192), 16, 0, 0); } while (0)
; #define PG8_LDA(dst, b, h) do { _Pragma("unroll") for (int m = 0; m < 4; ++m) _Pragma("unroll") for (int k = 0; k < 2; ++k) dst[m][k] = *(const PG8_LAS bf16x8*)(lds + PG8_SA(b, h) + aoff + m * 2048 + k * 1024); } while (0)
; #define PG8_MMA(ai, bj, At, Bt) do { __builtin_amdgcn_s_setprio(1); _Pragma("unroll") for (int m = 0; m < 4; ++m) _Pragma("unroll") for (int n = 0; n < 2; ++n) _Pragma("unroll") for (int k = 0; k < 2; ++k) \
;         acc[ai][bj][m][n] = __builtin_amdgcn_mfma_f32_16x16x32_bf16(Bt[n][k], At[m][k], acc[ai][bj][m][n], 0, 0, 0); __builtin_amdgcn_s_setprio(0); } while (0)
; #define PG8_WAIT_V(n) asm volatile("s_waitcnt vmcnt(" #n ")" ::: "memory")
; #define PG8_WAIT_L(n) asm volatile("s_waitcnt lgkmcnt(" #n ")" ::: "memory")
; #define PG8_BAR __builtin_amdgcn_s_barrier()
; #define PG8_SCHED __builtin_amdgcn_sched_barrier(0)
; template <class Epi, class Sched, bool ALIGN_EPI = false, bool SP2 = false>
; __device__ __forceinline__ void gemm_phase(PG8_LAS unsigned char* lds, const Gemm g, const Sched& S, const Epi& E) {
;     ...
;         for (int t = 0; t < nt; t += 2) {
;     ...
;             PG8_WAIT_V(8); PG8_WAIT_L(0); PG8_BAR; PG8_MMA(0, 0, At, B0); PG8_MMA(0, 1, At, B1); PG8_BAR; PG8_SCHED;
;             PG8_LDA(At, 1, 1); PG8_STAGE(PG8_SB(1, 0), b3, voffB); PG8_STAGE(PG8_SB(1, 1), b3 + hstep, voffB); PG8_STAGE(PG8_SA(1, 0), a3, voffA);
;             PG8_WAIT_V(8); PG8_WAIT_L(0); PG8_BAR; PG8_MMA(1, 0, At, B0); PG8_MMA(1, 1, At, B1); PG8_BAR; PG8_SCHED;
	s_waitcnt lgkmcnt(0)
	v_mfma_f32_16x16x32_bf16 v[124:127], v[138:141], v[192:195], v[124:127]
	v_mfma_f32_16x16x32_bf16 v[120:123], v[168:171], v[192:195], v[120:123]
	v_mfma_f32_16x16x32_bf16 v[108:111], v[138:141], v[200:203], v[108:111]
	v_mfma_f32_16x16x32_bf16 v[104:107], v[168:171], v[200:203], v[104:107]
	v_mfma_f32_16x16x32_bf16 v[92:95], v[138:141], v[208:211], v[92:95]
	v_mfma_f32_16x16x32_bf16 v[88:91], v[168:171], v[208:211], v[88:91]
	v_mfma_f32_16x16x32_bf16 v[76:79], v[138:141], v[216:219], v[76:79]
	v_mfma_f32_16x16x32_bf16 v[72:75], v[168:171], v[216:219], v[72:75]
	v_mfma_f32_16x16x32_bf16 v[124:127], v[142:145], v[196:199], v[124:127]
	v_mfma_f32_16x16x32_bf16 v[120:123], v[172:175], v[196:199], v[120:123]
	v_mfma_f32_16x16x32_bf16 v[108:111], v[142:145], v[204:207], v[108:111]
	v_mfma_f32_16x16x32_bf16 v[104:107], v[172:175], v[204:207], v[104:107]
	v_mfma_f32_16x16x32_bf16 v[92:95], v[142:145], v[212:215], v[92:95]
	v_mfma_f32_16x16x32_bf16 v[88:91], v[172:175], v[212:215], v[88:91]
	v_mfma_f32_16x16x32_bf16 v[76:79], v[142:145], v[220:223], v[76:79]
	v_mfma_f32_16x16x32_bf16 v[72:75], v[172:175], v[220:223], v[72:75]
	v_mfma_f32_16x16x32_bf16 v[116:119], v[176:179], v[192:195], v[116:119]
	v_mfma_f32_16x16x32_bf16 v[112:115], v[184:187], v[192:195], v[112:115]
	v_mfma_f32_16x16x32_bf16 v[100:103], v[176:179], v[200:203], v[100:103]
	v_mfma_f32_16x16x32_bf16 v[96:99], v[184:187], v[200:203], v[96:99]
	v_mfma_f32_16x16x32_bf16 v[84:87], v[176:179], v[208:211], v[84:87]
	v_mfma_f32_16x16x32_bf16 v[80:83], v[184:187], v[208:211], v[80:83]
	v_mfma_f32_16x16x32_bf16 v[68:71], v[176:179], v[216:219], v[68:71]
	v_mfma_f32_16x16x32_bf16 v[64:67], v[184:187], v[216:219], v[64:67]
	v_mfma_f32_16x16x32_bf16 v[116:119], v[180:183], v[196:199], v[116:119]
	v_mfma_f32_16x16x32_bf16 v[112:115], v[188:191], v[196:199], v[112:115]
	v_mfma_f32_16x16x32_bf16 v[100:103], v[180:183], v[204:207], v[100:103]
	v_mfma_f32_16x16x32_bf16 v[96:99], v[188:191], v[204:207], v[96:99]
	v_mfma_f32_16x16x32_bf16 v[84:87], v[180:183], v[212:215], v[84:87]
	v_mfma_f32_16x16x32_bf16 v[80:83], v[188:191], v[212:215], v[80:83]
	v_mfma_f32_16x16x32_bf16 v[68:71], v[180:183], v[220:223], v[68:71]
	v_mfma_f32_16x16x32_bf16 v[64:67], v[188:191], v[220:223], v[64:67]
	s_barrier
	s_add_i32 s14, s51, s21
	v_lshl_add_u64 v[146:147], v[146:147], 0, s[96:97]
	s_mov_b32 m0, s14
	ds_read_b128 v[192:195], v152 offset:49152
	ds_read_b128 v[196:199], v152 offset:50176
	ds_read_b128 v[200:203], v152 offset:51200
	ds_read_b128 v[204:207], v152 offset:52224
	ds_read_b128 v[208:211], v152 offset:53248
	ds_read_b128 v[212:215], v152 offset:54272
	ds_read_b128 v[216:219], v152 offset:55296
	ds_read_b128 v[220:223], v152 offset:56320
	global_load_lds_dwordx4 v[146:147], off
	s_add_i32 m0, s14, 0x2000
	s_add_u32 s12, s12, 0x40080
	v_lshl_add_u64 v[146:147], v[154:155], 0, s[96:97]
	s_addc_u32 s13, s13, 0
	s_add_i32 s14, s52, s21
	global_load_lds_dwordx4 v[146:147], off
	v_lshl_add_u64 v[146:147], s[12:13], 0, v[156:157]
	s_mov_b32 m0, s14
	s_nop 0
	global_load_lds_dwordx4 v[146:147], off
	v_lshl_add_u64 v[146:147], s[12:13], 0, v[128:129]
	s_add_i32 m0, s14, 0x2000
	s_nop 0
	global_load_lds_dwordx4 v[146:147], off
	v_lshl_add_u64 v[146:147], v[224:225], 0, s[96:97]
	s_mov_b32 m0, s29
	s_nop 0
	global_load_lds_dwordx4 v[146:147], off
	v_lshl_add_u64 v[146:147], v[226:227], 0, s[96:97]
	s_mov_b32 m0, s30
	s_nop 0
	global_load_lds_dwordx4 v[146:147], off
	s_waitcnt vmcnt(8)
	s_waitcnt lgkmcnt(0)
	s_barrier
	s_waitcnt lgkmcnt(0)
	v_mfma_f32_16x16x32_bf16 v[60:63], v[138:141], v[192:195], v[60:63]
	v_mfma_f32_16x16x32_bf16 v[56:59], v[168:171], v[192:195], v[56:59]
	v_mfma_f32_16x16x32_bf16 v[44:47], v[138:141], v[200:203], v[44:47]
	v_mfma_f32_16x16x32_bf16 v[40:43], v[168:171], v[200:203], v[40:43]
	v_mfma_f32_16x16x32_bf16 v[28:31], v[138:141], v[208:211], v[28:31]
	v_mfma_f32_16x16x32_bf16 v[24:27], v[168:171], v[208:211], v[24:27]
	v_mfma_f32_16x16x32_bf16 v[12:15], v[138:141], v[216:219], v[12:15]
	v_mfma_f32_16x16x32_bf16 v[8:11], v[168:171], v[216:219], v[8:11]
	v_mfma_f32_16x16x32_bf16 v[60:63], v[142:145], v[196:199], v[60:63]
	v_mfma_f32_16x16x32_bf16 v[56:59], v[172:175], v[196:199], v[56:59]
	v_mfma_f32_16x16x32_bf16 v[44:47], v[142:145], v[204:207], v[44:47]
	v_mfma_f32_16x16x32_bf16 v[40:43], v[172:175], v[204:207], v[40:43]
	v_mfma_f32_16x16x32_bf16 v[28:31], v[142:145], v[212:215], v[28:31]
	v_mfma_f32_16x16x32_bf16 v[24:27], v[172:175], v[212:215], v[24:27]
	v_mfma_f32_16x16x32_bf16 v[12:15], v[142:145], v[220:223], v[12:15]
	v_mfma_f32_16x16x32_bf16 v[8:11], v[172:175], v[220:223], v[8:11]
	v_mfma_f32_16x16x32_bf16 v[52:55], v[176:179], v[192:195], v[52:55]
	v_mfma_f32_16x16x32_bf16 v[48:51], v[184:187], v[192:195], v[48:51]
	v_mfma_f32_16x16x32_bf16 v[36:39], v[176:179], v[200:203], v[36:39]
	v_mfma_f32_16x16x32_bf16 v[32:35], v[184:187], v[200:203], v[32:35]
	v_mfma_f32_16x16x32_bf16 v[20:23], v[176:179], v[208:211], v[20:23]
	v_mfma_f32_16x16x32_bf16 v[16:19], v[184:187], v[208:211], v[16:19]
	v_mfma_f32_16x16x32_bf16 v[4:7], v[176:179], v[216:219], v[4:7]
	v_mfma_f32_16x16x32_bf16 v[0:3], v[184:187], v[216:219], v[0:3]
	v_mfma_f32_16x16x32_bf16 v[52:55], v[180:183], v[196:199], v[52:55]
	v_mfma_f32_16x16x32_bf16 v[48:51], v[188:191], v[196:199], v[48:51]
	v_mfma_f32_16x16x32_bf16 v[36:39], v[180:183], v[204:207], v[36:39]
	v_mfma_f32_16x16x32_bf16 v[32:35], v[188:191], v[204:207], v[32:35]
	v_mfma_f32_16x16x32_bf16 v[20:23], v[180:183], v[212:215], v[20:23]
	v_mfma_f32_16x16x32_bf16 v[16:19], v[188:191], v[212:215], v[16:19]
	v_mfma_f32_16x16x32_bf16 v[4:7], v[180:183], v[220:223], v[4:7]
	v_mfma_f32_16x16x32_bf16 v[0:3], v[188:191], v[220:223], v[0:3]
	s_barrier
	s_add_i32 s50, s50, 2
	s_add_u32 s10, s10, 0x100
	s_addc_u32 s11, s11, 0
	s_add_u32 s48, s48, 0x100
	s_addc_u32 s49, s49, 0
	s_branch .LBB0_399
